# v38 + the four GEMM K-loop heads aligned to 64 bytes
# speedup vs baseline: 1.0069x; 1.0069x over previous
; template <class Epi, class Sched, bool ALIGN_EPI = false, bool SP2 = false>
; __device__ __forceinline__ void gemm_phase(PG8_LAS unsigned char* lds, const Gemm g, const Sched& S, const Epi& E) {
;     ...
;         const bool has_next = S.next(ui + 1, nxt);
;         const char* nA = has_next ? (const char*)g.A + (size_t)nxt.pm * tstep : cA; const char* nB = has_next ? (const char*)g.Bt + (size_t)nxt.pn * tstep : cB;
;         for (int t = 0; t < nt; t += 2) {
;             const bool last = (t == nt - 2);
;             const char* a1 = cA + (size_t)(t + 1) * kstep;
;             const char* a2 = last ? nA : cA + (size_t)(t + 2) * kstep; const char* b2 = last ? nB : cB + (size_t)(t + 2) * kstep;
;             const char* a3 = a2 + kstep; const char* b3 = b2 + kstep;
;     ...
;         for (int a = 0; a < 2; ++a)
; #pragma unroll
;             for (int b = 0; b < 2; ++b)
; #pragma unroll
;                 for (int m = 0; m < 4; ++m)
; #pragma unroll
;                     for (int n = 0; n < 2; ++n) acc[a][b][m][n] = (f32x4){0.f, 0.f, 0.f, 0.f};
.LBB0_236:
	s_ashr_i32 s13, s12, 31
	s_lshl_b64 s[14:15], s[12:13], 19
	s_add_u32 s14, s0, s14
	s_addc_u32 s15, s1, s15
	s_and_b64 s[16:17], s[38:39], exec
	s_cselect_b32 s13, s15, s43
	s_cselect_b32 s19, s14, s42
	s_ashr_i32 s11, s10, 31
	s_lshl_b64 s[16:17], s[10:11], 19
	s_add_u32 s16, s35, s16
	s_addc_u32 s17, s48, s17
	s_and_b64 s[46:47], s[38:39], exec
	s_cselect_b32 s11, s17, s45
	s_cselect_b32 s41, s16, s44
	s_add_u32 s42, s42, 0x40080
	s_addc_u32 s43, s43, 0
	s_add_u32 s60, s44, 0x100
	v_mov_b32_e32 v0, 0
	s_addc_u32 s61, s45, 0
	s_mov_b32 s62, -2
	v_mov_b32_e32 v1, v0
	v_mov_b32_e32 v2, v0
	v_mov_b32_e32 v3, v0
	v_mov_b32_e32 v4, v0
	v_mov_b32_e32 v5, v0
	v_mov_b32_e32 v6, v0
	v_mov_b32_e32 v7, v0
	v_mov_b32_e32 v12, v0
	v_mov_b32_e32 v13, v0
	v_mov_b32_e32 v14, v0
	v_mov_b32_e32 v15, v0
	v_mov_b32_e32 v20, v0
	v_mov_b32_e32 v21, v0
	v_mov_b32_e32 v22, v0
	v_mov_b32_e32 v23, v0
	v_mov_b32_e32 v28, v0
	v_mov_b32_e32 v29, v0
	v_mov_b32_e32 v30, v0
	v_mov_b32_e32 v31, v0
	v_mov_b32_e32 v36, v0
	v_mov_b32_e32 v37, v0
	v_mov_b32_e32 v38, v0
	v_mov_b32_e32 v39, v0
	v_mov_b32_e32 v48, v0
	v_mov_b32_e32 v49, v0
	v_mov_b32_e32 v50, v0
	v_mov_b32_e32 v51, v0
	v_mov_b32_e32 v52, v0
	v_mov_b32_e32 v53, v0
	v_mov_b32_e32 v54, v0
	v_mov_b32_e32 v55, v0
	v_mov_b32_e32 v8, v0
	v_mov_b32_e32 v9, v0
	v_mov_b32_e32 v10, v0
	v_mov_b32_e32 v11, v0
	v_mov_b32_e32 v16, v0
	v_mov_b32_e32 v17, v0
	v_mov_b32_e32 v18, v0
	v_mov_b32_e32 v19, v0
	v_mov_b32_e32 v24, v0
	v_mov_b32_e32 v25, v0
	v_mov_b32_e32 v26, v0
	v_mov_b32_e32 v27, v0
	v_mov_b32_e32 v32, v0
	v_mov_b32_e32 v33, v0
	v_mov_b32_e32 v34, v0
	v_mov_b32_e32 v35, v0
	v_mov_b32_e32 v40, v0
	v_mov_b32_e32 v41, v0
	v_mov_b32_e32 v42, v0
	v_mov_b32_e32 v43, v0
	v_mov_b32_e32 v44, v0
	v_mov_b32_e32 v45, v0
	v_mov_b32_e32 v46, v0
	v_mov_b32_e32 v47, v0
	v_mov_b32_e32 v56, v0
	v_mov_b32_e32 v57, v0
	v_mov_b32_e32 v58, v0
	v_mov_b32_e32 v59, v0
	v_mov_b32_e32 v60, v0
	v_mov_b32_e32 v61, v0
	v_mov_b32_e32 v62, v0
	v_mov_b32_e32 v63, v0
	v_mov_b32_e32 v64, v0
	v_mov_b32_e32 v65, v0
	v_mov_b32_e32 v66, v0
	v_mov_b32_e32 v67, v0
	v_mov_b32_e32 v68, v0
	v_mov_b32_e32 v69, v0
	v_mov_b32_e32 v70, v0
	v_mov_b32_e32 v71, v0
	v_mov_b32_e32 v76, v0
	v_mov_b32_e32 v77, v0
	v_mov_b32_e32 v78, v0
	v_mov_b32_e32 v79, v0
	v_mov_b32_e32 v84, v0
	v_mov_b32_e32 v85, v0
	v_mov_b32_e32 v86, v0
	v_mov_b32_e32 v87, v0
	v_mov_b32_e32 v92, v0
	v_mov_b32_e32 v93, v0
	v_mov_b32_e32 v94, v0
	v_mov_b32_e32 v95, v0
	v_mov_b32_e32 v100, v0
	v_mov_b32_e32 v101, v0
	v_mov_b32_e32 v102, v0
	v_mov_b32_e32 v103, v0
	v_mov_b32_e32 v112, v0
	v_mov_b32_e32 v113, v0
	v_mov_b32_e32 v114, v0
	v_mov_b32_e32 v115, v0
	v_mov_b32_e32 v116, v0
	v_mov_b32_e32 v117, v0
	v_mov_b32_e32 v118, v0
	v_mov_b32_e32 v119, v0
	v_mov_b32_e32 v72, v0
	v_mov_b32_e32 v73, v0
	v_mov_b32_e32 v74, v0
	v_mov_b32_e32 v75, v0
	v_mov_b32_e32 v80, v0
	v_mov_b32_e32 v81, v0
	v_mov_b32_e32 v82, v0
	v_mov_b32_e32 v83, v0
	v_mov_b32_e32 v88, v0
	v_mov_b32_e32 v89, v0
	v_mov_b32_e32 v90, v0
	v_mov_b32_e32 v91, v0
	v_mov_b32_e32 v96, v0
	v_mov_b32_e32 v97, v0
	v_mov_b32_e32 v98, v0
	v_mov_b32_e32 v99, v0
	v_mov_b32_e32 v104, v0
	v_mov_b32_e32 v105, v0
	v_mov_b32_e32 v106, v0
	v_mov_b32_e32 v107, v0
	v_mov_b32_e32 v108, v0
	v_mov_b32_e32 v109, v0
	v_mov_b32_e32 v110, v0
	v_mov_b32_e32 v111, v0
	v_mov_b32_e32 v120, v0
	v_mov_b32_e32 v121, v0
	v_mov_b32_e32 v122, v0
	v_mov_b32_e32 v123, v0
	v_mov_b32_e32 v124, v0
	v_mov_b32_e32 v125, v0
	v_mov_b32_e32 v126, v0
	v_mov_b32_e32 v127, v0
	.p2align 6

; template <class Epi, class Sched, bool ALIGN_EPI = false, bool SP2 = false>
; __device__ __forceinline__ void gemm_phase(PG8_LAS unsigned char* lds, const Gemm g, const Sched& S, const Epi& E) {
;     ...
;         for (int t = 0; t < nt; t += 2) {
;     ...
;         for (int a = 0; a < 2; ++a)
; #pragma unroll
;             for (int b = 0; b < 2; ++b)
; #pragma unroll
;                 for (int m = 0; m < 4; ++m)
; #pragma unroll
;                     for (int n = 0; n < 2; ++n) acc[a][b][m][n] = (f32x4){0.f, 0.f, 0.f, 0.f};
.LBB0_263:
	s_add_u32 s29, s12, 0x100
	v_mov_b32_e32 v0, 0
	s_addc_u32 s30, s13, 0
	s_mov_b32 s31, -2
	v_mov_b32_e32 v1, v0
	v_mov_b32_e32 v2, v0
	v_mov_b32_e32 v3, v0
	v_mov_b32_e32 v4, v0
	s_waitcnt lgkmcnt(0)
	v_mov_b32_e32 v5, v0
	v_mov_b32_e32 v6, v0
	v_mov_b32_e32 v7, v0
	v_mov_b32_e32 v16, v0
	v_mov_b32_e32 v17, v0
	v_mov_b32_e32 v18, v0
	v_mov_b32_e32 v19, v0
	v_mov_b32_e32 v20, v0
	v_mov_b32_e32 v21, v0
	v_mov_b32_e32 v22, v0
	v_mov_b32_e32 v23, v0
	v_mov_b32_e32 v32, v0
	v_mov_b32_e32 v33, v0
	v_mov_b32_e32 v34, v0
	v_mov_b32_e32 v35, v0
	v_mov_b32_e32 v36, v0
	v_mov_b32_e32 v37, v0
	v_mov_b32_e32 v38, v0
	v_mov_b32_e32 v39, v0
	v_mov_b32_e32 v48, v0
	v_mov_b32_e32 v49, v0
	v_mov_b32_e32 v50, v0
	v_mov_b32_e32 v51, v0
	v_mov_b32_e32 v52, v0
	v_mov_b32_e32 v53, v0
	v_mov_b32_e32 v54, v0
	v_mov_b32_e32 v55, v0
	v_mov_b32_e32 v8, v0
	v_mov_b32_e32 v9, v0
	v_mov_b32_e32 v10, v0
	v_mov_b32_e32 v11, v0
	v_mov_b32_e32 v12, v0
	v_mov_b32_e32 v13, v0
	v_mov_b32_e32 v14, v0
	v_mov_b32_e32 v15, v0
	v_mov_b32_e32 v24, v0
	v_mov_b32_e32 v25, v0
	v_mov_b32_e32 v26, v0
	v_mov_b32_e32 v27, v0
	v_mov_b32_e32 v28, v0
	v_mov_b32_e32 v29, v0
	v_mov_b32_e32 v30, v0
	v_mov_b32_e32 v31, v0
	v_mov_b32_e32 v40, v0
	v_mov_b32_e32 v41, v0
	v_mov_b32_e32 v42, v0
	v_mov_b32_e32 v43, v0
	v_mov_b32_e32 v44, v0
	v_mov_b32_e32 v45, v0
	v_mov_b32_e32 v46, v0
	v_mov_b32_e32 v47, v0
	v_mov_b32_e32 v56, v0
	v_mov_b32_e32 v57, v0
	v_mov_b32_e32 v58, v0
	v_mov_b32_e32 v59, v0
	v_mov_b32_e32 v60, v0
	v_mov_b32_e32 v61, v0
	v_mov_b32_e32 v62, v0
	v_mov_b32_e32 v63, v0
	s_waitcnt vmcnt(0)
	v_mov_b32_e32 v64, v0
	v_mov_b32_e32 v65, v0
	v_mov_b32_e32 v66, v0
	v_mov_b32_e32 v67, v0
	v_mov_b32_e32 v68, v0
	v_mov_b32_e32 v69, v0
	v_mov_b32_e32 v70, v0
	v_mov_b32_e32 v71, v0
	v_mov_b32_e32 v80, v0
	v_mov_b32_e32 v81, v0
	v_mov_b32_e32 v82, v0
	v_mov_b32_e32 v83, v0
	v_mov_b32_e32 v84, v0
	v_mov_b32_e32 v85, v0
	v_mov_b32_e32 v86, v0
	v_mov_b32_e32 v87, v0
	v_mov_b32_e32 v96, v0
	v_mov_b32_e32 v97, v0
	v_mov_b32_e32 v98, v0
	v_mov_b32_e32 v99, v0
	v_mov_b32_e32 v100, v0
	v_mov_b32_e32 v101, v0
	v_mov_b32_e32 v102, v0
	v_mov_b32_e32 v103, v0
	v_mov_b32_e32 v116, v0
	v_mov_b32_e32 v117, v0
	v_mov_b32_e32 v118, v0
	v_mov_b32_e32 v119, v0
	v_mov_b32_e32 v124, v0
	v_mov_b32_e32 v125, v0
	v_mov_b32_e32 v126, v0
	v_mov_b32_e32 v127, v0
	v_mov_b32_e32 v72, v0
	v_mov_b32_e32 v73, v0
	v_mov_b32_e32 v74, v0
	v_mov_b32_e32 v75, v0
	v_mov_b32_e32 v76, v0
	v_mov_b32_e32 v77, v0
	v_mov_b32_e32 v78, v0
	v_mov_b32_e32 v79, v0
	v_mov_b32_e32 v88, v0
	v_mov_b32_e32 v89, v0
	v_mov_b32_e32 v90, v0
	v_mov_b32_e32 v91, v0
	v_mov_b32_e32 v92, v0
	v_mov_b32_e32 v93, v0
	v_mov_b32_e32 v94, v0
	v_mov_b32_e32 v95, v0
	v_mov_b32_e32 v108, v0
	v_mov_b32_e32 v109, v0
	v_mov_b32_e32 v110, v0
	v_mov_b32_e32 v111, v0
	v_mov_b32_e32 v112, v0
	v_mov_b32_e32 v113, v0
	v_mov_b32_e32 v114, v0
	v_mov_b32_e32 v115, v0
	v_mov_b32_e32 v140, v0
	v_mov_b32_e32 v141, v0
	v_mov_b32_e32 v142, v0
	v_mov_b32_e32 v143, v0
	v_mov_b32_e32 v144, v0
	v_mov_b32_e32 v145, v0
	v_mov_b32_e32 v146, v0
	v_mov_b32_e32 v147, v0
	.p2align 6

; template <class Epi, class Sched, bool ALIGN_EPI = false, bool SP2 = false>
; __device__ __forceinline__ void gemm_phase(PG8_LAS unsigned char* lds, const Gemm g, const Sched& S, const Epi& E) {
;     ...
;         const bool has_next = S.next(ui + 1, nxt);
;         const char* nA = has_next ? (const char*)g.A + (size_t)nxt.pm * tstep : cA; const char* nB = has_next ? (const char*)g.Bt + (size_t)nxt.pn * tstep : cB;
;         for (int t = 0; t < nt; t += 2) {
;             const bool last = (t == nt - 2);
;             const char* a1 = cA + (size_t)(t + 1) * kstep;
;             const char* a2 = last ? nA : cA + (size_t)(t + 2) * kstep; const char* b2 = last ? nB : cB + (size_t)(t + 2) * kstep;
;             const char* a3 = a2 + kstep; const char* b3 = b2 + kstep;
;     ...
;         for (int a = 0; a < 2; ++a)
; #pragma unroll
;             for (int b = 0; b < 2; ++b)
; #pragma unroll
;                 for (int m = 0; m < 4; ++m)
; #pragma unroll
;                     for (int n = 0; n < 2; ++n) acc[a][b][m][n] = (f32x4){0.f, 0.f, 0.f, 0.f};
.LBB0_355:
	s_ashr_i32 s47, s46, 31
	s_lshl_b64 s[10:11], s[46:47], 19
	s_add_u32 s48, s92, s10
	s_addc_u32 s49, s93, s11
	s_and_b64 s[10:11], s[40:41], exec
	s_cselect_b32 s29, s49, s7
	s_cselect_b32 s30, s48, s6
	s_ashr_i32 s45, s44, 31
	s_lshl_b64 s[10:11], s[44:45], 19
	s_add_u32 s50, s12, s10
	s_addc_u32 s51, s13, s11
	s_and_b64 s[10:11], s[40:41], exec
	s_cselect_b32 s31, s51, s9
	s_cselect_b32 s34, s50, s8
	s_add_u32 s6, s6, 0x40080
	s_addc_u32 s7, s7, 0
	s_add_u32 s35, s8, 0x100
	v_mov_b32_e32 v0, 0
	s_addc_u32 s45, s9, 0
	s_mov_b32 s47, -2
	v_mov_b32_e32 v1, v0
	v_mov_b32_e32 v2, v0
	v_mov_b32_e32 v3, v0
	v_mov_b32_e32 v4, v0
	v_mov_b32_e32 v5, v0
	v_mov_b32_e32 v6, v0
	s_waitcnt lgkmcnt(0)
	v_mov_b32_e32 v7, v0
	v_mov_b32_e32 v16, v0
	v_mov_b32_e32 v17, v0
	v_mov_b32_e32 v18, v0
	v_mov_b32_e32 v19, v0
	v_mov_b32_e32 v20, v0
	v_mov_b32_e32 v21, v0
	v_mov_b32_e32 v22, v0
	v_mov_b32_e32 v23, v0
	v_mov_b32_e32 v32, v0
	v_mov_b32_e32 v33, v0
	v_mov_b32_e32 v34, v0
	v_mov_b32_e32 v35, v0
	v_mov_b32_e32 v36, v0
	v_mov_b32_e32 v37, v0
	v_mov_b32_e32 v38, v0
	v_mov_b32_e32 v39, v0
	v_mov_b32_e32 v48, v0
	v_mov_b32_e32 v49, v0
	v_mov_b32_e32 v50, v0
	v_mov_b32_e32 v51, v0
	v_mov_b32_e32 v52, v0
	v_mov_b32_e32 v53, v0
	v_mov_b32_e32 v54, v0
	v_mov_b32_e32 v55, v0
	v_mov_b32_e32 v8, v0
	v_mov_b32_e32 v9, v0
	v_mov_b32_e32 v10, v0
	v_mov_b32_e32 v11, v0
	v_mov_b32_e32 v12, v0
	v_mov_b32_e32 v13, v0
	v_mov_b32_e32 v14, v0
	v_mov_b32_e32 v15, v0
	v_mov_b32_e32 v24, v0
	v_mov_b32_e32 v25, v0
	v_mov_b32_e32 v26, v0
	v_mov_b32_e32 v27, v0
	v_mov_b32_e32 v28, v0
	v_mov_b32_e32 v29, v0
	v_mov_b32_e32 v30, v0
	v_mov_b32_e32 v31, v0
	v_mov_b32_e32 v40, v0
	v_mov_b32_e32 v41, v0
	v_mov_b32_e32 v42, v0
	v_mov_b32_e32 v43, v0
	v_mov_b32_e32 v44, v0
	v_mov_b32_e32 v45, v0
	v_mov_b32_e32 v46, v0
	v_mov_b32_e32 v47, v0
	v_mov_b32_e32 v56, v0
	v_mov_b32_e32 v57, v0
	v_mov_b32_e32 v58, v0
	v_mov_b32_e32 v59, v0
	v_mov_b32_e32 v60, v0
	v_mov_b32_e32 v61, v0
	v_mov_b32_e32 v62, v0
	v_mov_b32_e32 v63, v0
	s_waitcnt vmcnt(0)
	v_mov_b32_e32 v64, v0
	v_mov_b32_e32 v65, v0
	v_mov_b32_e32 v66, v0
	v_mov_b32_e32 v67, v0
	v_mov_b32_e32 v68, v0
	v_mov_b32_e32 v69, v0
	v_mov_b32_e32 v70, v0
	v_mov_b32_e32 v71, v0
	v_mov_b32_e32 v80, v0
	v_mov_b32_e32 v81, v0
	v_mov_b32_e32 v82, v0
	v_mov_b32_e32 v83, v0
	v_mov_b32_e32 v84, v0
	v_mov_b32_e32 v85, v0
	v_mov_b32_e32 v86, v0
	v_mov_b32_e32 v87, v0
	v_mov_b32_e32 v96, v0
	v_mov_b32_e32 v97, v0
	v_mov_b32_e32 v98, v0
	v_mov_b32_e32 v99, v0
	v_mov_b32_e32 v100, v0
	v_mov_b32_e32 v101, v0
	v_mov_b32_e32 v102, v0
	v_mov_b32_e32 v103, v0
	v_mov_b32_e32 v120, v0
	v_mov_b32_e32 v121, v0
	v_mov_b32_e32 v122, v0
	v_mov_b32_e32 v123, v0
	v_mov_b32_e32 v124, v0
	v_mov_b32_e32 v125, v0
	v_mov_b32_e32 v126, v0
	v_mov_b32_e32 v127, v0
	v_mov_b32_e32 v72, v0
	v_mov_b32_e32 v73, v0
	v_mov_b32_e32 v74, v0
	v_mov_b32_e32 v75, v0
	v_mov_b32_e32 v76, v0
	v_mov_b32_e32 v77, v0
	v_mov_b32_e32 v78, v0
	v_mov_b32_e32 v79, v0
	v_mov_b32_e32 v88, v0
	v_mov_b32_e32 v89, v0
	v_mov_b32_e32 v90, v0
	v_mov_b32_e32 v91, v0
	v_mov_b32_e32 v92, v0
	v_mov_b32_e32 v93, v0
	v_mov_b32_e32 v94, v0
	v_mov_b32_e32 v95, v0
	v_mov_b32_e32 v108, v0
	v_mov_b32_e32 v109, v0
	v_mov_b32_e32 v110, v0
	v_mov_b32_e32 v111, v0
	v_mov_b32_e32 v112, v0
	v_mov_b32_e32 v113, v0
	v_mov_b32_e32 v114, v0
	v_mov_b32_e32 v115, v0
	v_mov_b32_e32 v148, v0
	v_mov_b32_e32 v149, v0
	v_mov_b32_e32 v150, v0
	v_mov_b32_e32 v151, v0
	v_mov_b32_e32 v152, v0
	v_mov_b32_e32 v153, v0
	v_mov_b32_e32 v154, v0
	v_mov_b32_e32 v155, v0
	.p2align 6

; template <class Epi, class Sched, bool ALIGN_EPI = false, bool SP2 = false>
; __device__ __forceinline__ void gemm_phase(PG8_LAS unsigned char* lds, const Gemm g, const Sched& S, const Epi& E) {
;     ...
;         const bool has_next = S.next(ui + 1, nxt);
;         const char* nA = has_next ? (const char*)g.A + (size_t)nxt.pm * tstep : cA; const char* nB = has_next ? (const char*)g.Bt + (size_t)nxt.pn * tstep : cB;
;         for (int t = 0; t < nt; t += 2) {
;             const bool last = (t == nt - 2);
;             const char* a1 = cA + (size_t)(t + 1) * kstep;
;             const char* a2 = last ? nA : cA + (size_t)(t + 2) * kstep; const char* b2 = last ? nB : cB + (size_t)(t + 2) * kstep;
;             const char* a3 = a2 + kstep; const char* b3 = b2 + kstep;
;     ...
;         for (int a = 0; a < 2; ++a)
; #pragma unroll
;             for (int b = 0; b < 2; ++b)
; #pragma unroll
;                 for (int m = 0; m < 4; ++m)
; #pragma unroll
;                     for (int n = 0; n < 2; ++n) acc[a][b][m][n] = (f32x4){0.f, 0.f, 0.f, 0.f};
.LBB0_398:
	s_ashr_i32 s41, s40, 31
	s_lshl_b64 s[14:15], s[40:41], 19
	s_add_u32 s42, s0, s14
	s_addc_u32 s43, s1, s15
	s_and_b64 s[14:15], s[38:39], exec
	s_cselect_b32 s41, s43, s11
	s_cselect_b32 s46, s42, s10
	s_ashr_i32 s9, s8, 31
	s_lshl_b64 s[14:15], s[8:9], 19
	s_add_u32 s44, s19, s14
	s_addc_u32 s45, s20, s15
	s_and_b64 s[14:15], s[38:39], exec
	s_cselect_b32 s9, s45, s13
	s_cselect_b32 s47, s44, s12
	s_add_u32 s10, s10, 0x40080
	s_addc_u32 s11, s11, 0
	s_add_u32 s48, s12, 0x100
	v_mov_b32_e32 v0, 0
	s_addc_u32 s49, s13, 0
	s_mov_b32 s50, -2
	v_mov_b32_e32 v1, v0
	v_mov_b32_e32 v2, v0
	v_mov_b32_e32 v3, v0
	v_mov_b32_e32 v4, v0
	v_mov_b32_e32 v5, v0
	v_mov_b32_e32 v6, v0
	v_mov_b32_e32 v7, v0
	v_mov_b32_e32 v16, v0
	v_mov_b32_e32 v17, v0
	v_mov_b32_e32 v18, v0
	v_mov_b32_e32 v19, v0
	v_mov_b32_e32 v20, v0
	v_mov_b32_e32 v21, v0
	v_mov_b32_e32 v22, v0
	v_mov_b32_e32 v23, v0
	v_mov_b32_e32 v32, v0
	v_mov_b32_e32 v33, v0
	v_mov_b32_e32 v34, v0
	v_mov_b32_e32 v35, v0
	v_mov_b32_e32 v36, v0
	v_mov_b32_e32 v37, v0
	v_mov_b32_e32 v38, v0
	v_mov_b32_e32 v39, v0
	v_mov_b32_e32 v48, v0
	v_mov_b32_e32 v49, v0
	v_mov_b32_e32 v50, v0
	v_mov_b32_e32 v51, v0
	v_mov_b32_e32 v52, v0
	v_mov_b32_e32 v53, v0
	v_mov_b32_e32 v54, v0
	v_mov_b32_e32 v55, v0
	v_mov_b32_e32 v8, v0
	v_mov_b32_e32 v9, v0
	v_mov_b32_e32 v10, v0
	v_mov_b32_e32 v11, v0
	v_mov_b32_e32 v12, v0
	v_mov_b32_e32 v13, v0
	v_mov_b32_e32 v14, v0
	v_mov_b32_e32 v15, v0
	v_mov_b32_e32 v24, v0
	v_mov_b32_e32 v25, v0
	v_mov_b32_e32 v26, v0
	v_mov_b32_e32 v27, v0
	v_mov_b32_e32 v28, v0
	v_mov_b32_e32 v29, v0
	v_mov_b32_e32 v30, v0
	v_mov_b32_e32 v31, v0
	v_mov_b32_e32 v40, v0
	v_mov_b32_e32 v41, v0
	v_mov_b32_e32 v42, v0
	v_mov_b32_e32 v43, v0
	v_mov_b32_e32 v44, v0
	v_mov_b32_e32 v45, v0
	v_mov_b32_e32 v46, v0
	v_mov_b32_e32 v47, v0
	v_mov_b32_e32 v56, v0
	v_mov_b32_e32 v57, v0
	v_mov_b32_e32 v58, v0
	v_mov_b32_e32 v59, v0
	v_mov_b32_e32 v60, v0
	v_mov_b32_e32 v61, v0
	v_mov_b32_e32 v62, v0
	v_mov_b32_e32 v63, v0
	v_mov_b32_e32 v64, v0
	v_mov_b32_e32 v65, v0
	v_mov_b32_e32 v66, v0
	v_mov_b32_e32 v67, v0
	v_mov_b32_e32 v68, v0
	v_mov_b32_e32 v69, v0
	v_mov_b32_e32 v70, v0
	v_mov_b32_e32 v71, v0
	v_mov_b32_e32 v80, v0
	v_mov_b32_e32 v81, v0
	v_mov_b32_e32 v82, v0
	v_mov_b32_e32 v83, v0
	v_mov_b32_e32 v84, v0
	v_mov_b32_e32 v85, v0
	v_mov_b32_e32 v86, v0
	v_mov_b32_e32 v87, v0
	v_mov_b32_e32 v96, v0
	v_mov_b32_e32 v97, v0
	v_mov_b32_e32 v98, v0
	v_mov_b32_e32 v99, v0
	v_mov_b32_e32 v100, v0
	v_mov_b32_e32 v101, v0
	v_mov_b32_e32 v102, v0
	v_mov_b32_e32 v103, v0
	v_mov_b32_e32 v112, v0
	v_mov_b32_e32 v113, v0
	v_mov_b32_e32 v114, v0
	v_mov_b32_e32 v115, v0
	v_mov_b32_e32 v116, v0
	v_mov_b32_e32 v117, v0
	v_mov_b32_e32 v118, v0
	v_mov_b32_e32 v119, v0
	v_mov_b32_e32 v72, v0
	v_mov_b32_e32 v73, v0
	v_mov_b32_e32 v74, v0
	v_mov_b32_e32 v75, v0
	v_mov_b32_e32 v76, v0
	v_mov_b32_e32 v77, v0
	v_mov_b32_e32 v78, v0
	v_mov_b32_e32 v79, v0
	v_mov_b32_e32 v88, v0
	v_mov_b32_e32 v89, v0
	v_mov_b32_e32 v90, v0
	v_mov_b32_e32 v91, v0
	v_mov_b32_e32 v92, v0
	v_mov_b32_e32 v93, v0
	v_mov_b32_e32 v94, v0
	v_mov_b32_e32 v95, v0
	v_mov_b32_e32 v104, v0
	v_mov_b32_e32 v105, v0
	v_mov_b32_e32 v106, v0
	v_mov_b32_e32 v107, v0
	v_mov_b32_e32 v108, v0
	v_mov_b32_e32 v109, v0
	v_mov_b32_e32 v110, v0
	v_mov_b32_e32 v111, v0
	v_mov_b32_e32 v120, v0
	v_mov_b32_e32 v121, v0
	v_mov_b32_e32 v122, v0
	v_mov_b32_e32 v123, v0
	v_mov_b32_e32 v124, v0
	v_mov_b32_e32 v125, v0
	v_mov_b32_e32 v126, v0
	v_mov_b32_e32 v127, v0
	.p2align 6
